# v52 + norm1 row loop waits only for the prefetched x row (not the previous row's write-through stores)
# speedup vs baseline: 1.0218x; 1.0001x over previous
.Lp1_keep:
	s_waitcnt vmcnt(4)
